# hybrid release: attention/LRU-pass-1 phase keeps write-back stores and its barrier alone does the L2 write-back; all other phases write-through without one
# baseline (speedup 1.0000x reference)
.Lnb_loc_done_r:
	s_cmp_eq_u32 s38, 4
	s_cbranch_scc1 .Lnb_wb_r
	s_cmp_eq_u32 s38, 12
	s_cbranch_scc0 .Lnb_nowb_r
.Lnb_wb_r:
	buffer_wbl2 sc1
.Lnb_nowb_r:
	s_waitcnt vmcnt(0)
	v_mov_b32_e32 v6, 1
	v_mov_b32_e32 v12, 0x3400
	global_atomic_add v12, v6, s[6:7]
